# w_out / w_mlp_in / w_mlp_out bf16 transposes moved from phase 0 into 256 work-queue items behind the combine chunks
# baseline (speedup 1.0000x reference)
; #define LAS __attribute__((address_space(3)))
; __global__ void __launch_bounds__(512, 2) mega(Params p) {
;   extern __shared__ __attribute__((aligned(16))) char shm_raw[];
;   cg::grid_group grid = cg::this_grid();
;   volatile LAS unsigned* st = (volatile LAS unsigned*)((LAS unsigned char*)shm_raw + 131072 + 3072);
;   if (threadIdx.x == 0) { st[0] = 0u; st[1] = 0u; st[2] = 0u; st[3] = 0u; }
;   __syncthreads();
_Z4mega6Params:
	v_writelane_b32 v236, s0, 20
	v_writelane_b32 v236, s1, 21
	s_load_dword s3, s[0:1], 0x84
	s_load_dword s80, s[0:1], 0x90
	s_load_dwordx2 s[76:77], s[0:1], 0x88
	s_add_u32 s6, s0, 0x88
	v_and_b32_e32 v202, 0x3ff, v0
	s_addc_u32 s7, s1, 0
	v_cmp_eq_u32_e64 s[84:85], 0, v202
	s_and_saveexec_b64 s[4:5], s[84:85]
	s_cbranch_execz .LBB0_2
	s_add_i32 s8, 0, 0x20c00
	v_mov_b32_e32 v1, 0
	v_mov_b32_e32 v2, s8
	s_add_i32 s8, 0, 0x20c04
	ds_write_b32 v2, v1
	v_mov_b32_e32 v2, s8
	s_add_i32 s8, 0, 0x20c08
	ds_write_b32 v2, v1
	v_mov_b32_e32 v2, s8
	s_add_i32 s8, 0, 0x20c0c
	ds_write_b32 v2, v1
	v_mov_b32_e32 v2, s8
	ds_write_b32 v2, v1

; DI void phase_prep(const Params& p) {
;     ...
;   const int gthreads = gridDim.x * 512, gtid = blockIdx.x * 512 + tid;
;   transpose_w(p.w_in, 1024, 4096, (bf16_t*)(p.ws + WS_WIN), gtid, gthreads);
;   transpose_w(p.w_out, 1024, 1024, (bf16_t*)(p.ws + WS_WOUT), gtid, gthreads);
;   transpose_w(p.w_mlp_in, 1024, 4096, (bf16_t*)(p.ws + WS_WM1), gtid, gthreads);
;   transpose_w(p.w_mlp_out, 4096, 1024, (bf16_t*)(p.ws + WS_WM2), gtid, gthreads);
;   bf16_t* H = (bf16_t*)(p.ws + WS_H);
;   for (int tok = (blockIdx.x * 8 + wave) * 2; tok < NTOK; tok += gridDim.x * 16) rms_row2_bf16(xrow(p, tok), p.attn_norm_w, H + (size_t)tok * 1024, lane);
.LBB0_39:
	v_lshrrev_b32_e32 v0, 5, v202
	v_and_b32_e32 v0, 30, v0
	s_add_u32 s44, s58, 0x2000000
	v_lshl_add_u32 v4, s2, 4, v0
	s_mov_b32 s0, 0x10000
	s_addc_u32 s45, s59, 0
	v_cmp_gt_i32_e32 vcc, s0, v4
	v_mbcnt_lo_u32_b32 v145, -1, 0
	s_and_saveexec_b64 s[4:5], vcc
	s_cbranch_execz .LBB0_42
	v_and_b32_e32 v12, 63, v202
	v_lshlrev_b32_e32 v6, 4, v12
	s_waitcnt lgkmcnt(0)
	global_load_dwordx4 v[0:3], v6, s[64:65]
	v_mbcnt_hi_u32_b32 v5, -1, v145
	v_and_b32_e32 v8, 64, v5
	v_add_u32_e32 v8, 64, v8
	v_xor_b32_e32 v9, 32, v5
	v_cmp_lt_i32_e32 vcc, v9, v8
	v_mov_b32_e32 v7, 0
	s_lshl_b32 s3, s76, 4
	v_cndmask_b32_e32 v9, v5, v9, vcc
	v_lshlrev_b32_e32 v13, 2, v9
	v_xor_b32_e32 v9, 16, v5
	v_cmp_lt_i32_e32 vcc, v9, v8
	s_mov_b64 s[6:7], 0
	s_mov_b32 s9, 0x8000
	v_cndmask_b32_e32 v9, v5, v9, vcc
	v_lshlrev_b32_e32 v14, 2, v9
	v_xor_b32_e32 v9, 8, v5
	v_cmp_lt_i32_e32 vcc, v9, v8
	v_mov_b32_e32 v19, s63
	v_mov_b32_e32 v20, s61
	v_cndmask_b32_e32 v9, v5, v9, vcc
	v_lshlrev_b32_e32 v15, 2, v9
	v_xor_b32_e32 v9, 4, v5
	v_cmp_lt_i32_e32 vcc, v9, v8
	v_mov_b32_e32 v21, s62
	v_mov_b32_e32 v22, s60
	v_cndmask_b32_e32 v9, v5, v9, vcc
	v_lshlrev_b32_e32 v16, 2, v9
	v_xor_b32_e32 v9, 2, v5
	v_cmp_lt_i32_e32 vcc, v9, v8
	s_movk_i32 s10, 0x1000
	s_mov_b32 s8, 0x3a800000
	v_cndmask_b32_e32 v9, v5, v9, vcc
	v_lshlrev_b32_e32 v17, 2, v9
	v_xor_b32_e32 v9, 1, v5
	v_cmp_lt_i32_e32 vcc, v9, v8
	s_mov_b32 s11, 0x800000
	s_mov_b32 s12, 0xffff
	v_cndmask_b32_e32 v5, v5, v9, vcc
	v_lshl_add_u64 v[8:9], s[64:65], 0, v[6:7]
	v_lshlrev_b32_e32 v6, 3, v12
	v_lshlrev_b32_e32 v18, 2, v5
	v_lshl_add_u64 v[10:11], s[44:45], 0, v[6:7]
	v_lshlrev_b32_e32 v6, 4, v12
	v_mov_b32_e32 v12, 0x358637bd
	global_load_dwordx4 v[24:27], v[8:9], off offset:1024
	global_load_dwordx4 v[28:31], v[8:9], off offset:2048
	global_load_dwordx4 v[32:35], v[8:9], off offset:3072
	v_readfirstlane_b32 s98, v4
	v_add_u32_e32 v23, 0xffff8000, v4
	v_ashrrev_i32_e32 v5, 31, v4
	v_cmp_gt_i32_e32 vcc, s9, v4
	v_lshlrev_b64 v[40:41], 11, v[4:5]
	s_nop 1
	v_cndmask_b32_e32 v37, 0, v5, vcc
	v_cndmask_b32_e32 v36, v23, v4, vcc
	v_cndmask_b32_e32 v39, v19, v20, vcc
	v_cndmask_b32_e32 v38, v21, v22, vcc
	v_lshlrev_b64 v[36:37], 12, v[36:37]
	v_lshl_add_u64 v[36:37], v[38:39], 0, v[36:37]
	v_lshl_add_u64 v[52:53], v[36:37], 0, v[6:7]
	v_lshl_add_u64 v[68:69], v[10:11], 0, v[40:41]
	v_add_co_u32_e32 v70, vcc, s10, v52
	s_nop 1
	v_addc_co_u32_e32 v71, vcc, 0, v53, vcc
	global_load_dwordx4 v[76:79], v[52:53], off
	global_load_dwordx4 v[80:83], v[52:53], off offset:1024
	global_load_dwordx4 v[84:87], v[52:53], off offset:2048
	global_load_dwordx4 v[88:91], v[52:53], off offset:3072
	global_load_dwordx4 v[92:95], v[70:71], off
	global_load_dwordx4 v[96:99], v[70:71], off offset:1024
	global_load_dwordx4 v[100:103], v[70:71], off offset:2048
	global_load_dwordx4 v[104:107], v[70:71], off offset:3072
	s_waitcnt vmcnt(0)
	s_branch .Lr0_entry

; DI unsigned cvt_pk_bf16(float lo, float hi) { unsigned r; asm("v_cvt_pk_bf16_f32 %0, %1, %2" : "=v"(r) : "v"(lo), "v"(hi)); return r; }
; DI void transpose_w(const float* __restrict__ W, int K, int N, bf16_t* __restrict__ Wt, int gtid, int gthreads) {
;   const int total = (K / 8) * N;
;   for (int id = gtid; id < total; id += gthreads) {
;     const int kc = id / N, n = id - kc * N;
;     const int rho = n & 255;
;     const int act = (n & ~255) + ((rho >> 5) & 3) * 64 + (rho >> 7) * 32 + ((rho >> 2) & 3) * 8 + ((rho >> 4) & 1) * 4 + (rho & 3);
;     const float* src = W + (size_t)(kc * 8) * N + act;
;     float v[8];
; #pragma unroll
;     for (int j = 0; j < 8; ++j) v[j] = src[(size_t)j * N];
;     uint4 o; o.x = cvt_pk_bf16(v[0], v[1]); o.y = cvt_pk_bf16(v[2], v[3]); o.z = cvt_pk_bf16(v[4], v[5]); o.w = cvt_pk_bf16(v[6], v[7]);
;     *(uint4*)(Wt + (size_t)n * K + kc * 8) = o;
;   }
; }
.Ltq_dispatch:
	s_cmpk_gt_i32 s12, 2863
	s_cbranch_scc1 .LBB0_953
	v_readlane_b32 s4, v236, 20
	v_readlane_b32 s5, v236, 21
	s_sub_i32 s3, s12, 2608
	v_lshl_add_u32 v0, s3, 9, v202
	s_nop 3
	s_load_dwordx2 s[6:7], s[4:5], 0x50
	s_load_dwordx4 s[8:11], s[4:5], 0x60
	v_and_b32_e32 v1, 0x3ff, v0
	v_lshrrev_b32_e32 v2, 10, v0
	v_and_b32_e32 v3, 0xffffff03, v1
	v_and_b32_e32 v9, 0x60, v1
	v_lshl_or_b32 v3, v9, 1, v3
	v_and_b32_e32 v9, 0x0c, v1
	v_lshl_or_b32 v3, v9, 1, v3
	v_bfe_u32 v9, v1, 7, 1
	v_lshl_or_b32 v3, v9, 5, v3
	v_bfe_u32 v9, v1, 4, 1
	v_lshl_or_b32 v3, v9, 2, v3
	v_lshlrev_b32_e32 v3, 2, v3
	v_lshl_or_b32 v3, v2, 15, v3
	v_lshlrev_b32_e32 v2, 4, v2
	v_lshl_or_b32 v4, v1, 11, v2
	v_lshl_or_b32 v5, v1, 13, v2
	v_add_u32_e32 v4, 0x800000, v4
	v_add_u32_e32 v5, 0x1200000, v5
	v_and_b32_e32 v1, 0xfff, v0
	v_lshrrev_b32_e32 v2, 12, v0
	v_and_b32_e32 v6, 0xffffff03, v1
	v_and_b32_e32 v9, 0x60, v1
	v_lshl_or_b32 v6, v9, 1, v6
	v_and_b32_e32 v9, 0x0c, v1
	v_lshl_or_b32 v6, v9, 1, v6
	v_bfe_u32 v9, v1, 7, 1
	v_lshl_or_b32 v6, v9, 5, v6
	v_bfe_u32 v9, v1, 4, 1
	v_lshl_or_b32 v6, v9, 2, v6
	v_lshlrev_b32_e32 v6, 2, v6
	v_lshl_or_b32 v6, v2, 17, v6
	v_lshlrev_b32_e32 v2, 4, v2
	v_lshl_or_b32 v7, v1, 11, v2
	v_add_u32_e32 v7, 0xa00000, v7
	s_waitcnt lgkmcnt(0)
	global_load_dword v16, v3, s[6:7]
	v_add_u32_e32 v49, 0x1000, v3
	global_load_dword v17, v49, s[6:7]
	v_add_u32_e32 v50, 0x2000, v3
	global_load_dword v18, v50, s[6:7]
	v_add_u32_e32 v51, 0x3000, v3
	global_load_dword v19, v51, s[6:7]
	v_add_u32_e32 v52, 0x4000, v3
	global_load_dword v20, v52, s[6:7]
	v_add_u32_e32 v53, 0x5000, v3
	global_load_dword v21, v53, s[6:7]
	v_add_u32_e32 v54, 0x6000, v3
	global_load_dword v22, v54, s[6:7]
	v_add_u32_e32 v55, 0x7000, v3
	global_load_dword v23, v55, s[6:7]
	global_load_dword v24, v6, s[8:9]
	v_add_u32_e32 v49, 0x4000, v6
	global_load_dword v25, v49, s[8:9]
	v_add_u32_e32 v50, 0x8000, v6
	global_load_dword v26, v50, s[8:9]
	v_add_u32_e32 v51, 0xc000, v6
	global_load_dword v27, v51, s[8:9]
	v_add_u32_e32 v52, 0x10000, v6
	global_load_dword v28, v52, s[8:9]
	v_add_u32_e32 v53, 0x14000, v6
	global_load_dword v29, v53, s[8:9]
	v_add_u32_e32 v54, 0x18000, v6
	global_load_dword v30, v54, s[8:9]
	v_add_u32_e32 v55, 0x1c000, v6
	global_load_dword v31, v55, s[8:9]
	v_add_u32_e32 v48, 0x400000, v6
	global_load_dword v32, v48, s[8:9]
	v_add_u32_e32 v49, 0x404000, v6
	global_load_dword v33, v49, s[8:9]
	v_add_u32_e32 v50, 0x408000, v6
	global_load_dword v34, v50, s[8:9]
	v_add_u32_e32 v51, 0x40c000, v6
	global_load_dword v35, v51, s[8:9]
	v_add_u32_e32 v52, 0x410000, v6
	global_load_dword v36, v52, s[8:9]
	v_add_u32_e32 v53, 0x414000, v6
	global_load_dword v37, v53, s[8:9]
	v_add_u32_e32 v54, 0x418000, v6
	global_load_dword v38, v54, s[8:9]
	v_add_u32_e32 v55, 0x41c000, v6
	global_load_dword v39, v55, s[8:9]
	v_add_u32_e32 v48, 0x800000, v6
	global_load_dword v40, v48, s[8:9]
	v_add_u32_e32 v49, 0x804000, v6
	global_load_dword v41, v49, s[8:9]
	v_add_u32_e32 v50, 0x808000, v6
	global_load_dword v42, v50, s[8:9]
	v_add_u32_e32 v51, 0x80c000, v6
	global_load_dword v43, v51, s[8:9]
	v_add_u32_e32 v52, 0x810000, v6
	global_load_dword v44, v52, s[8:9]
	v_add_u32_e32 v53, 0x814000, v6
	global_load_dword v45, v53, s[8:9]
	v_add_u32_e32 v54, 0x818000, v6
	global_load_dword v46, v54, s[8:9]
	v_add_u32_e32 v55, 0x81c000, v6
	global_load_dword v47, v55, s[8:9]
	s_waitcnt vmcnt(24)
	v_cvt_pk_bf16_f32 v56, v16, v17
	v_cvt_pk_bf16_f32 v57, v18, v19
	v_cvt_pk_bf16_f32 v58, v20, v21
	v_cvt_pk_bf16_f32 v59, v22, v23
	global_store_dwordx4 v4, v[56:59], s[58:59]
	v_add_u32_e32 v48, 0xc00000, v6
	global_load_dword v16, v48, s[8:9]
	v_add_u32_e32 v49, 0xc04000, v6
	global_load_dword v17, v49, s[8:9]
	v_add_u32_e32 v50, 0xc08000, v6
	global_load_dword v18, v50, s[8:9]
	v_add_u32_e32 v51, 0xc0c000, v6
	global_load_dword v19, v51, s[8:9]
	v_add_u32_e32 v52, 0xc10000, v6
	global_load_dword v20, v52, s[8:9]
	v_add_u32_e32 v53, 0xc14000, v6
	global_load_dword v21, v53, s[8:9]
	v_add_u32_e32 v54, 0xc18000, v6
	global_load_dword v22, v54, s[8:9]
	v_add_u32_e32 v55, 0xc1c000, v6
	global_load_dword v23, v55, s[8:9]
	s_waitcnt vmcnt(25)
; DI unsigned cvt_pk_bf16(float lo, float hi) { unsigned r; asm("v_cvt_pk_bf16_f32 %0, %1, %2" : "=v"(r) : "v"(lo), "v"(hi)); return r; }
; DI void transpose_w(const float* __restrict__ W, int K, int N, bf16_t* __restrict__ Wt, int gtid, int gthreads) {
;   const int total = (K / 8) * N;
;   for (int id = gtid; id < total; id += gthreads) {
;     const int kc = id / N, n = id - kc * N;
;     const int rho = n & 255;
;     const int act = (n & ~255) + ((rho >> 5) & 3) * 64 + (rho >> 7) * 32 + ((rho >> 2) & 3) * 8 + ((rho >> 4) & 1) * 4 + (rho & 3);
;     const float* src = W + (size_t)(kc * 8) * N + act;
;     float v[8];
; #pragma unroll
;     for (int j = 0; j < 8; ++j) v[j] = src[(size_t)j * N];
;     uint4 o; o.x = cvt_pk_bf16(v[0], v[1]); o.y = cvt_pk_bf16(v[2], v[3]); o.z = cvt_pk_bf16(v[4], v[5]); o.w = cvt_pk_bf16(v[6], v[7]);
;     *(uint4*)(Wt + (size_t)n * K + kc * 8) = o;
;   }
; }
	v_cvt_pk_bf16_f32 v60, v24, v25
	v_cvt_pk_bf16_f32 v61, v26, v27
	v_cvt_pk_bf16_f32 v62, v28, v29
	v_cvt_pk_bf16_f32 v63, v30, v31
	global_store_dwordx4 v7, v[60:63], s[58:59]
	global_load_dword v24, v3, s[10:11]
	v_add_u32_e32 v49, 0x1000, v3
	global_load_dword v25, v49, s[10:11]
	v_add_u32_e32 v50, 0x2000, v3
	global_load_dword v26, v50, s[10:11]
	v_add_u32_e32 v51, 0x3000, v3
	global_load_dword v27, v51, s[10:11]
	v_add_u32_e32 v52, 0x4000, v3
	global_load_dword v28, v52, s[10:11]
	v_add_u32_e32 v53, 0x5000, v3
	global_load_dword v29, v53, s[10:11]
	v_add_u32_e32 v54, 0x6000, v3
	global_load_dword v30, v54, s[10:11]
	v_add_u32_e32 v55, 0x7000, v3
	global_load_dword v31, v55, s[10:11]
	s_waitcnt vmcnt(26)
	v_cvt_pk_bf16_f32 v56, v32, v33
	v_cvt_pk_bf16_f32 v57, v34, v35
	v_cvt_pk_bf16_f32 v58, v36, v37
	v_cvt_pk_bf16_f32 v59, v38, v39
	v_add_u32_e32 v10, 0x200, v7
	global_store_dwordx4 v10, v[56:59], s[58:59]
	v_add_u32_e32 v48, 0x400000, v3
	global_load_dword v32, v48, s[10:11]
	v_add_u32_e32 v49, 0x401000, v3
	global_load_dword v33, v49, s[10:11]
	v_add_u32_e32 v50, 0x402000, v3
	global_load_dword v34, v50, s[10:11]
	v_add_u32_e32 v51, 0x403000, v3
	global_load_dword v35, v51, s[10:11]
	v_add_u32_e32 v52, 0x404000, v3
	global_load_dword v36, v52, s[10:11]
	v_add_u32_e32 v53, 0x405000, v3
	global_load_dword v37, v53, s[10:11]
	v_add_u32_e32 v54, 0x406000, v3
	global_load_dword v38, v54, s[10:11]
	v_add_u32_e32 v55, 0x407000, v3
	global_load_dword v39, v55, s[10:11]
	s_waitcnt vmcnt(27)
	v_cvt_pk_bf16_f32 v60, v40, v41
	v_cvt_pk_bf16_f32 v61, v42, v43
	v_cvt_pk_bf16_f32 v62, v44, v45
	v_cvt_pk_bf16_f32 v63, v46, v47
	v_add_u32_e32 v10, 0x400, v7
	global_store_dwordx4 v10, v[60:63], s[58:59]
	v_add_u32_e32 v48, 0x800000, v3
	global_load_dword v40, v48, s[10:11]
	v_add_u32_e32 v49, 0x801000, v3
	global_load_dword v41, v49, s[10:11]
	v_add_u32_e32 v50, 0x802000, v3
	global_load_dword v42, v50, s[10:11]
	v_add_u32_e32 v51, 0x803000, v3
	global_load_dword v43, v51, s[10:11]
	v_add_u32_e32 v52, 0x804000, v3
	global_load_dword v44, v52, s[10:11]
	v_add_u32_e32 v53, 0x805000, v3
	global_load_dword v45, v53, s[10:11]
	v_add_u32_e32 v54, 0x806000, v3
	global_load_dword v46, v54, s[10:11]
	v_add_u32_e32 v55, 0x807000, v3
	global_load_dword v47, v55, s[10:11]
	s_waitcnt vmcnt(27)
	v_cvt_pk_bf16_f32 v56, v16, v17
	v_cvt_pk_bf16_f32 v57, v18, v19
	v_cvt_pk_bf16_f32 v58, v20, v21
	v_cvt_pk_bf16_f32 v59, v22, v23
	v_add_u32_e32 v10, 0x600, v7
	global_store_dwordx4 v10, v[56:59], s[58:59]
	v_add_u32_e32 v48, 0xc00000, v3
	global_load_dword v16, v48, s[10:11]
	v_add_u32_e32 v49, 0xc01000, v3
	global_load_dword v17, v49, s[10:11]
	v_add_u32_e32 v50, 0xc02000, v3
	global_load_dword v18, v50, s[10:11]
	v_add_u32_e32 v51, 0xc03000, v3
	global_load_dword v19, v51, s[10:11]
	v_add_u32_e32 v52, 0xc04000, v3
	global_load_dword v20, v52, s[10:11]
	v_add_u32_e32 v53, 0xc05000, v3
	global_load_dword v21, v53, s[10:11]
	v_add_u32_e32 v54, 0xc06000, v3
	global_load_dword v22, v54, s[10:11]
	v_add_u32_e32 v55, 0xc07000, v3
	global_load_dword v23, v55, s[10:11]
	s_waitcnt vmcnt(27)
	v_cvt_pk_bf16_f32 v60, v24, v25
	v_cvt_pk_bf16_f32 v61, v26, v27
	v_cvt_pk_bf16_f32 v62, v28, v29
	v_cvt_pk_bf16_f32 v63, v30, v31
	global_store_dwordx4 v5, v[60:63], s[58:59]
	s_waitcnt vmcnt(19)
	v_cvt_pk_bf16_f32 v56, v32, v33
	v_cvt_pk_bf16_f32 v57, v34, v35
	v_cvt_pk_bf16_f32 v58, v36, v37
	v_cvt_pk_bf16_f32 v59, v38, v39
	v_add_u32_e32 v10, 0x800, v5
	global_store_dwordx4 v10, v[56:59], s[58:59]
	s_waitcnt vmcnt(11)
	v_cvt_pk_bf16_f32 v60, v40, v41
	v_cvt_pk_bf16_f32 v61, v42, v43
	v_cvt_pk_bf16_f32 v62, v44, v45
	v_cvt_pk_bf16_f32 v63, v46, v47
	v_add_u32_e32 v10, 0x1000, v5
	global_store_dwordx4 v10, v[60:63], s[58:59]
	s_waitcnt vmcnt(3)
	v_cvt_pk_bf16_f32 v56, v16, v17
	v_cvt_pk_bf16_f32 v57, v18, v19
	v_cvt_pk_bf16_f32 v58, v20, v21
	v_cvt_pk_bf16_f32 v59, v22, v23
	v_add_u32_e32 v10, 0x1800, v5
	global_store_dwordx4 v10, v[56:59], s[58:59]
	s_branch .LBB0_952
